# K/V^T GEMM epilogue: seven one-dword touch loads pull the lane's whole row-partials block into L1 before the 16 serial per-row rstd chains
# baseline (speedup 1.0000x reference)
.LBB0_176:
	s_lshl_b32 s1, s20, 8
	s_lshl_b32 s10, s50, 6
	v_mbcnt_lo_u32_b32 v0, -1, 0
	v_mbcnt_hi_u32_b32 v0, -1, v0
	s_add_i32 s5, s10, s1
	s_lshl_b32 s1, s19, 8
	s_lshl_b32 s11, s58, 5
	v_and_b32_e32 v131, 15, v0
	v_ashrrev_i32_e32 v0, 4, v0
	s_add_i32 s11, s11, s1
	v_lshl_add_u32 v130, v0, 3, s11
	v_lshlrev_b32_e32 v0, 2, v0
	v_and_b32_e32 v0, 4, v0
	v_sub_u32_e32 v162, v130, v0
	v_and_or_b32 v0, s10, 64, v131
	v_ashrrev_i32_e32 v131, 31, v130
	v_lshlrev_b64 v[132:133], 6, v[130:131]
	v_lshl_add_u64 v[158:159], s[68:69], 0, v[132:133]
	global_load_dwordx4 v[132:135], v[158:159], off offset:16
	global_load_dwordx4 v[136:139], v[158:159], off offset:48
	global_load_dwordx4 v[140:143], v[158:159], off
	global_load_dwordx4 v[164:167], v[158:159], off offset:32
	global_load_dword v174, v[158:159], off offset:128
	global_load_dword v175, v[158:159], off offset:256
	global_load_dword v180, v[158:159], off offset:384
	v_mov_b32_e32 v178, 0x2000
	v_mov_b32_e32 v179, 0
	v_lshl_add_u64 v[176:177], v[158:159], 0, v[178:179]
	global_load_dword v181, v[176:177], off
	global_load_dword v182, v[176:177], off offset:128
	global_load_dword v183, v[176:177], off offset:256
	global_load_dword v184, v[176:177], off offset:384
	s_ashr_i32 s1, s5, 7
	v_readlane_b32 s12, v251, 18
	v_readlane_b32 s13, v251, 19
	v_lshlrev_b32_e32 v0, 7, v0
	s_addk_i32 s5, 0x80
	s_ashr_i32 s5, s5, 7
	s_movk_i32 s3, 0x2000
	s_waitcnt vmcnt(0)
	v_mov_b32_e32 v144, v140
	v_mov_b32_e32 v145, v164
	v_mov_b32_e32 v164, v141
	v_pk_add_f32 v[140:141], v[144:145], v[164:165]
	v_mov_b32_e32 v144, v142
	v_mov_b32_e32 v145, v166
	v_mov_b32_e32 v166, v143
	v_pk_add_f32 v[142:143], v[144:145], v[166:167]
	s_nop 0
	v_pk_add_f32 v[140:141], v[140:141], v[142:143]
	v_mov_b32_e32 v142, v132
	v_mov_b32_e32 v143, v136
	v_mov_b32_e32 v136, v133
	v_pk_add_f32 v[132:133], v[142:143], v[136:137]
	v_mov_b32_e32 v136, v134
	v_mov_b32_e32 v137, v138
	v_mov_b32_e32 v138, v135
	v_pk_add_f32 v[134:135], v[136:137], v[138:139]
	s_nop 0
	v_pk_add_f32 v[132:133], v[132:133], v[134:135]
	s_nop 0
	v_pk_add_f32 v[132:133], v[140:141], v[132:133]
	s_nop 0
	v_add_f32_e32 v131, v132, v133
	v_fmamk_f32 v131, v131, 0x3a800000, v240
	v_cmp_gt_f32_e32 vcc, s31, v131
	v_mul_f32_e32 v132, 0x4f800000, v131
	s_nop 0
	v_cndmask_b32_e32 v131, v131, v132, vcc
	v_sqrt_f32_e32 v132, v131
	s_nop 0
	v_add_u32_e32 v133, -1, v132
	v_fma_f32 v134, -v133, v132, v131
	v_cmp_ge_f32_e64 s[40:41], 0, v134
	v_add_u32_e32 v134, 1, v132
	s_nop 0
	v_cndmask_b32_e64 v133, v132, v133, s[40:41]
	v_fma_f32 v132, -v134, v132, v131
	v_cmp_lt_f32_e64 s[40:41], 0, v132
	s_nop 1
	v_cndmask_b32_e64 v132, v133, v134, s[40:41]
	v_mul_f32_e32 v133, 0x37800000, v132
	v_cndmask_b32_e32 v132, v132, v133, vcc
	v_cmp_class_f32_e32 vcc, v131, v241
	s_nop 1
	v_cndmask_b32_e32 v163, v132, v131, vcc
	v_or_b32_e32 v132, 1, v130
	v_ashrrev_i32_e32 v133, 31, v132
	v_lshlrev_b64 v[132:133], 6, v[132:133]
	v_lshl_add_u64 v[144:145], s[68:69], 0, v[132:133]
	global_load_dwordx4 v[132:135], v[144:145], off offset:16
	global_load_dwordx4 v[136:139], v[144:145], off offset:48
	global_load_dwordx4 v[140:143], v[144:145], off
	global_load_dwordx4 v[164:167], v[144:145], off offset:32
	s_waitcnt vmcnt(1)
	v_mov_b32_e32 v144, v140
	s_waitcnt vmcnt(0)
	v_mov_b32_e32 v145, v164
	v_mov_b32_e32 v164, v141
	v_pk_add_f32 v[140:141], v[144:145], v[164:165]
	v_mov_b32_e32 v144, v142
	v_mov_b32_e32 v145, v166
	v_mov_b32_e32 v166, v143
	v_pk_add_f32 v[142:143], v[144:145], v[166:167]
	s_nop 0
	v_pk_add_f32 v[140:141], v[140:141], v[142:143]
	v_mov_b32_e32 v142, v132
	v_mov_b32_e32 v143, v136
	v_mov_b32_e32 v136, v133
	v_pk_add_f32 v[132:133], v[142:143], v[136:137]
	v_mov_b32_e32 v136, v134
	v_mov_b32_e32 v137, v138
	v_mov_b32_e32 v138, v135
	v_pk_add_f32 v[134:135], v[136:137], v[138:139]
	s_nop 0
	v_pk_add_f32 v[132:133], v[132:133], v[134:135]
	s_nop 0
	v_pk_add_f32 v[132:133], v[140:141], v[132:133]
	s_nop 0
	v_add_f32_e32 v131, v132, v133
	v_fmamk_f32 v131, v131, 0x3a800000, v240
	v_cmp_gt_f32_e32 vcc, s31, v131
	v_mul_f32_e32 v132, 0x4f800000, v131
	s_nop 0
	v_cndmask_b32_e32 v131, v131, v132, vcc
	v_sqrt_f32_e32 v132, v131
	s_nop 0
	v_add_u32_e32 v133, -1, v132
	v_fma_f32 v134, -v133, v132, v131
	v_cmp_ge_f32_e64 s[40:41], 0, v134
	v_add_u32_e32 v134, 1, v132
	s_nop 0
	v_cndmask_b32_e64 v133, v132, v133, s[40:41]
	v_fma_f32 v132, -v134, v132, v131
	v_cmp_lt_f32_e64 s[40:41], 0, v132
	s_nop 1
	v_cndmask_b32_e64 v132, v133, v134, s[40:41]
	v_mul_f32_e32 v133, 0x37800000, v132
	v_cndmask_b32_e32 v132, v132, v133, vcc
	v_cmp_class_f32_e32 vcc, v131, v241
	s_nop 1
	v_cndmask_b32_e32 v164, v132, v131, vcc
	v_or_b32_e32 v132, 2, v130
	v_ashrrev_i32_e32 v133, 31, v132
	v_lshlrev_b64 v[132:133], 6, v[132:133]
	v_lshl_add_u64 v[144:145], s[68:69], 0, v[132:133]
	global_load_dwordx4 v[132:135], v[144:145], off offset:16
	global_load_dwordx4 v[136:139], v[144:145], off offset:48
	global_load_dwordx4 v[140:143], v[144:145], off
	global_load_dwordx4 v[166:169], v[144:145], off offset:32
	s_waitcnt vmcnt(1)
	v_mov_b32_e32 v144, v140
	s_waitcnt vmcnt(0)
	v_mov_b32_e32 v145, v166
	v_mov_b32_e32 v166, v141
	v_pk_add_f32 v[140:141], v[144:145], v[166:167]
	v_mov_b32_e32 v144, v142
	v_mov_b32_e32 v145, v168
	v_mov_b32_e32 v168, v143
	v_pk_add_f32 v[142:143], v[144:145], v[168:169]
	s_nop 0
	v_pk_add_f32 v[140:141], v[140:141], v[142:143]
	v_mov_b32_e32 v142, v132
	v_mov_b32_e32 v143, v136
	v_mov_b32_e32 v136, v133
	v_pk_add_f32 v[132:133], v[142:143], v[136:137]
	v_mov_b32_e32 v136, v134
	v_mov_b32_e32 v137, v138
	v_mov_b32_e32 v138, v135
	v_pk_add_f32 v[134:135], v[136:137], v[138:139]
	s_nop 0
	v_pk_add_f32 v[132:133], v[132:133], v[134:135]
	s_nop 0
	v_pk_add_f32 v[132:133], v[140:141], v[132:133]
	s_nop 0
	v_add_f32_e32 v131, v132, v133
	v_fmamk_f32 v131, v131, 0x3a800000, v240
	v_cmp_gt_f32_e32 vcc, s31, v131
	v_mul_f32_e32 v132, 0x4f800000, v131
	s_nop 0
	v_cndmask_b32_e32 v131, v131, v132, vcc
	v_sqrt_f32_e32 v132, v131
	s_nop 0
	v_add_u32_e32 v133, -1, v132
	v_fma_f32 v134, -v133, v132, v131
	v_cmp_ge_f32_e64 s[40:41], 0, v134
	v_add_u32_e32 v134, 1, v132
	s_nop 0
	v_cndmask_b32_e64 v133, v132, v133, s[40:41]
	v_fma_f32 v132, -v134, v132, v131
	v_cmp_lt_f32_e64 s[40:41], 0, v132
	s_nop 1
	v_cndmask_b32_e64 v132, v133, v134, s[40:41]
	v_mul_f32_e32 v133, 0x37800000, v132
	v_cndmask_b32_e32 v132, v132, v133, vcc
	v_cmp_class_f32_e32 vcc, v131, v241
	s_nop 1
	v_cndmask_b32_e32 v165, v132, v131, vcc
	v_or_b32_e32 v132, 3, v130
	v_ashrrev_i32_e32 v133, 31, v132
	v_lshlrev_b64 v[132:133], 6, v[132:133]
	v_lshl_add_u64 v[144:145], s[68:69], 0, v[132:133]
	global_load_dwordx4 v[132:135], v[144:145], off offset:16
	global_load_dwordx4 v[136:139], v[144:145], off offset:48
	global_load_dwordx4 v[140:143], v[144:145], off
	global_load_dwordx4 v[166:169], v[144:145], off offset:32
	s_waitcnt vmcnt(1)
	v_mov_b32_e32 v144, v140
	s_waitcnt vmcnt(0)
	v_mov_b32_e32 v145, v166
	v_mov_b32_e32 v166, v141
	v_pk_add_f32 v[140:141], v[144:145], v[166:167]
	v_mov_b32_e32 v144, v142
	v_mov_b32_e32 v145, v168
	v_mov_b32_e32 v168, v143
	v_pk_add_f32 v[142:143], v[144:145], v[168:169]
	s_nop 0
	v_pk_add_f32 v[140:141], v[140:141], v[142:143]
	v_mov_b32_e32 v142, v132
	v_mov_b32_e32 v143, v136
	v_mov_b32_e32 v136, v133
	v_pk_add_f32 v[132:133], v[142:143], v[136:137]
	v_mov_b32_e32 v136, v134
	v_mov_b32_e32 v137, v138
	v_mov_b32_e32 v138, v135
	v_pk_add_f32 v[134:135], v[136:137], v[138:139]
	s_nop 0
	v_pk_add_f32 v[132:133], v[132:133], v[134:135]
	s_nop 0
	v_pk_add_f32 v[132:133], v[140:141], v[132:133]
	s_nop 0
	v_add_f32_e32 v131, v132, v133
	v_fmamk_f32 v131, v131, 0x3a800000, v240
	v_cmp_gt_f32_e32 vcc, s31, v131
	v_mul_f32_e32 v132, 0x4f800000, v131
	s_nop 0
	v_cndmask_b32_e32 v131, v131, v132, vcc
	v_sqrt_f32_e32 v132, v131
	s_nop 0
	v_add_u32_e32 v133, -1, v132
	v_fma_f32 v134, -v133, v132, v131
	v_cmp_ge_f32_e64 s[40:41], 0, v134
	v_add_u32_e32 v134, 1, v132
	s_nop 0
	v_cndmask_b32_e64 v133, v132, v133, s[40:41]
	v_fma_f32 v132, -v134, v132, v131
	v_cmp_lt_f32_e64 s[40:41], 0, v132
	s_nop 1
	v_cndmask_b32_e64 v132, v133, v134, s[40:41]
	v_mul_f32_e32 v133, 0x37800000, v132
	v_cndmask_b32_e32 v132, v132, v133, vcc
	v_cmp_class_f32_e32 vcc, v131, v241
	s_nop 1
	v_cndmask_b32_e32 v166, v132, v131, vcc
	v_or_b32_e32 v132, 4, v130
	v_ashrrev_i32_e32 v133, 31, v132
	v_lshlrev_b64 v[132:133], 6, v[132:133]
	v_lshl_add_u64 v[144:145], s[68:69], 0, v[132:133]
	global_load_dwordx4 v[132:135], v[144:145], off offset:16
	global_load_dwordx4 v[136:139], v[144:145], off offset:48
	global_load_dwordx4 v[140:143], v[144:145], off
	global_load_dwordx4 v[168:171], v[144:145], off offset:32
	s_waitcnt vmcnt(1)
	v_mov_b32_e32 v144, v140
	s_waitcnt vmcnt(0)
	v_mov_b32_e32 v145, v168
	v_mov_b32_e32 v168, v141
	v_pk_add_f32 v[140:141], v[144:145], v[168:169]
	v_mov_b32_e32 v144, v142
	v_mov_b32_e32 v145, v170
	v_mov_b32_e32 v170, v143
	v_pk_add_f32 v[142:143], v[144:145], v[170:171]
	s_nop 0
	v_pk_add_f32 v[140:141], v[140:141], v[142:143]
	v_mov_b32_e32 v142, v132
	v_mov_b32_e32 v143, v136
	v_mov_b32_e32 v136, v133
	v_pk_add_f32 v[132:133], v[142:143], v[136:137]
	v_mov_b32_e32 v136, v134
	v_mov_b32_e32 v137, v138
	v_mov_b32_e32 v138, v135
	v_pk_add_f32 v[134:135], v[136:137], v[138:139]
	s_nop 0
	v_pk_add_f32 v[132:133], v[132:133], v[134:135]
	s_nop 0
	v_pk_add_f32 v[132:133], v[140:141], v[132:133]
	s_nop 0
	v_add_f32_e32 v131, v132, v133
	v_fmamk_f32 v131, v131, 0x3a800000, v240
	v_cmp_gt_f32_e32 vcc, s31, v131
	v_mul_f32_e32 v132, 0x4f800000, v131
	s_nop 0
	v_cndmask_b32_e32 v131, v131, v132, vcc
	v_sqrt_f32_e32 v132, v131
	s_nop 0
	v_add_u32_e32 v133, -1, v132
	v_fma_f32 v134, -v133, v132, v131
	v_cmp_ge_f32_e64 s[40:41], 0, v134
	v_add_u32_e32 v134, 1, v132
	s_nop 0
	v_cndmask_b32_e64 v133, v132, v133, s[40:41]
	v_fma_f32 v132, -v134, v132, v131
	v_cmp_lt_f32_e64 s[40:41], 0, v132
	s_nop 1
	v_cndmask_b32_e64 v132, v133, v134, s[40:41]
	v_mul_f32_e32 v133, 0x37800000, v132
	v_cndmask_b32_e32 v132, v132, v133, vcc
	v_cmp_class_f32_e32 vcc, v131, v241
	s_nop 1
	v_cndmask_b32_e32 v167, v132, v131, vcc
	v_or_b32_e32 v132, 5, v130
	v_ashrrev_i32_e32 v133, 31, v132
	v_lshlrev_b64 v[132:133], 6, v[132:133]
	v_lshl_add_u64 v[144:145], s[68:69], 0, v[132:133]
	global_load_dwordx4 v[132:135], v[144:145], off offset:16
	global_load_dwordx4 v[136:139], v[144:145], off offset:48
	global_load_dwordx4 v[140:143], v[144:145], off
	global_load_dwordx4 v[168:171], v[144:145], off offset:32
	s_waitcnt vmcnt(1)
	v_mov_b32_e32 v144, v140
	s_waitcnt vmcnt(0)
	v_mov_b32_e32 v145, v168
	v_mov_b32_e32 v168, v141
	v_pk_add_f32 v[140:141], v[144:145], v[168:169]
	v_mov_b32_e32 v144, v142
	v_mov_b32_e32 v145, v170
	v_mov_b32_e32 v170, v143
	v_pk_add_f32 v[142:143], v[144:145], v[170:171]
	s_nop 0
	v_pk_add_f32 v[140:141], v[140:141], v[142:143]
	v_mov_b32_e32 v142, v132
	v_mov_b32_e32 v143, v136
	v_mov_b32_e32 v136, v133
	v_pk_add_f32 v[132:133], v[142:143], v[136:137]
	v_mov_b32_e32 v136, v134
	v_mov_b32_e32 v137, v138
	v_mov_b32_e32 v138, v135
	v_pk_add_f32 v[134:135], v[136:137], v[138:139]
	s_nop 0
	v_pk_add_f32 v[132:133], v[132:133], v[134:135]
	s_nop 0
	v_pk_add_f32 v[132:133], v[140:141], v[132:133]
	s_nop 0
	v_add_f32_e32 v131, v132, v133
	v_fmamk_f32 v131, v131, 0x3a800000, v240
	v_cmp_gt_f32_e32 vcc, s31, v131
	v_mul_f32_e32 v132, 0x4f800000, v131
	s_nop 0
	v_cndmask_b32_e32 v131, v131, v132, vcc
	v_sqrt_f32_e32 v132, v131
	s_nop 0
	v_add_u32_e32 v133, -1, v132
	v_fma_f32 v134, -v133, v132, v131
	v_cmp_ge_f32_e64 s[40:41], 0, v134
	v_add_u32_e32 v134, 1, v132
	s_nop 0
	v_cndmask_b32_e64 v133, v132, v133, s[40:41]
	v_fma_f32 v132, -v134, v132, v131
	v_cmp_lt_f32_e64 s[40:41], 0, v132
	s_nop 1
	v_cndmask_b32_e64 v132, v133, v134, s[40:41]
	v_mul_f32_e32 v133, 0x37800000, v132
	v_cndmask_b32_e32 v132, v132, v133, vcc
	v_cmp_class_f32_e32 vcc, v131, v241
	s_nop 1
	v_cndmask_b32_e32 v168, v132, v131, vcc
	v_or_b32_e32 v132, 6, v130
	v_ashrrev_i32_e32 v133, 31, v132
	v_lshlrev_b64 v[132:133], 6, v[132:133]
	v_lshl_add_u64 v[144:145], s[68:69], 0, v[132:133]
	global_load_dwordx4 v[132:135], v[144:145], off offset:16
	global_load_dwordx4 v[136:139], v[144:145], off offset:48
	global_load_dwordx4 v[140:143], v[144:145], off
	global_load_dwordx4 v[170:173], v[144:145], off offset:32
	v_or_b32_e32 v130, 7, v130
	s_waitcnt vmcnt(1)
	v_mov_b32_e32 v144, v140
	s_waitcnt vmcnt(0)
	v_mov_b32_e32 v145, v170
	v_mov_b32_e32 v170, v141
	v_pk_add_f32 v[140:141], v[144:145], v[170:171]
	v_mov_b32_e32 v144, v142
	v_mov_b32_e32 v145, v172
	v_mov_b32_e32 v172, v143
	v_pk_add_f32 v[142:143], v[144:145], v[172:173]
	s_nop 0
	v_pk_add_f32 v[140:141], v[140:141], v[142:143]
	v_mov_b32_e32 v142, v132
	v_mov_b32_e32 v143, v136
	v_mov_b32_e32 v136, v133
	v_pk_add_f32 v[132:133], v[142:143], v[136:137]
	v_mov_b32_e32 v136, v134
	v_mov_b32_e32 v137, v138
	v_mov_b32_e32 v138, v135
	v_pk_add_f32 v[134:135], v[136:137], v[138:139]
	s_nop 0
	v_pk_add_f32 v[132:133], v[132:133], v[134:135]
	s_nop 0
	v_pk_add_f32 v[132:133], v[140:141], v[132:133]
	s_nop 0
	v_add_f32_e32 v131, v132, v133
	v_fmamk_f32 v131, v131, 0x3a800000, v240
	v_cmp_gt_f32_e32 vcc, s31, v131
	v_mul_f32_e32 v132, 0x4f800000, v131
	s_nop 0
	v_cndmask_b32_e32 v131, v131, v132, vcc
	v_sqrt_f32_e32 v132, v131
	s_nop 0
	v_add_u32_e32 v133, -1, v132
	v_fma_f32 v134, -v133, v132, v131
	v_cmp_ge_f32_e64 s[40:41], 0, v134
	v_add_u32_e32 v134, 1, v132
	s_nop 0
	v_cndmask_b32_e64 v133, v132, v133, s[40:41]
	v_fma_f32 v132, -v134, v132, v131
	v_cmp_lt_f32_e64 s[40:41], 0, v132
	s_nop 1
	v_cndmask_b32_e64 v132, v133, v134, s[40:41]
	v_mul_f32_e32 v133, 0x37800000, v132
	v_cndmask_b32_e32 v132, v132, v133, vcc
	v_cmp_class_f32_e32 vcc, v131, v241
	s_nop 1
	v_cndmask_b32_e32 v169, v132, v131, vcc
	v_ashrrev_i32_e32 v131, 31, v130
	v_lshlrev_b64 v[130:131], 6, v[130:131]
	v_lshl_add_u64 v[142:143], s[68:69], 0, v[130:131]
	global_load_dwordx4 v[134:137], v[142:143], off offset:16
	global_load_dwordx4 v[130:133], v[142:143], off offset:48
	global_load_dwordx4 v[138:141], v[142:143], off
	s_nop 0
	global_load_dwordx4 v[142:145], v[142:143], off offset:32
	s_waitcnt vmcnt(1)
	v_mov_b32_e32 v170, v138
	s_waitcnt vmcnt(0)
	v_mov_b32_e32 v171, v142
	v_mov_b32_e32 v142, v139
	v_pk_add_f32 v[138:139], v[170:171], v[142:143]
	v_mov_b32_e32 v142, v140
	v_mov_b32_e32 v143, v144
	v_mov_b32_e32 v144, v141
	v_pk_add_f32 v[140:141], v[142:143], v[144:145]
	v_and_b32_e32 v142, 60, v162
	v_pk_add_f32 v[138:139], v[138:139], v[140:141]
	v_mov_b32_e32 v140, v134
	v_mov_b32_e32 v141, v130
	v_mov_b32_e32 v130, v135
	v_mov_b32_e32 v134, v136
	v_mov_b32_e32 v135, v132
	v_mov_b32_e32 v132, v137
	v_pk_add_f32 v[130:131], v[140:141], v[130:131]
	v_pk_add_f32 v[132:133], v[134:135], v[132:133]
	v_bfe_u32 v141, v162, 6, 5
	v_pk_add_f32 v[130:131], v[130:131], v[132:133]
	s_nop 0
	v_pk_add_f32 v[130:131], v[138:139], v[130:131]
	s_nop 0
	v_add_f32_e32 v130, v130, v131
	v_fmamk_f32 v130, v130, 0x3a800000, v240
	v_cmp_gt_f32_e32 vcc, s31, v130
	v_mul_f32_e32 v131, 0x4f800000, v130
	s_nop 0
	v_cndmask_b32_e32 v130, v130, v131, vcc
	v_sqrt_f32_e32 v131, v130
	s_nop 0
	v_add_u32_e32 v132, -1, v131
	v_fma_f32 v133, -v132, v131, v130
	v_cmp_ge_f32_e64 s[40:41], 0, v133
	v_add_u32_e32 v133, 1, v131
	s_nop 0
	v_cndmask_b32_e64 v132, v131, v132, s[40:41]
	v_fma_f32 v131, -v133, v131, v130
	v_cmp_lt_f32_e64 s[40:41], 0, v131
	s_nop 1
	v_cndmask_b32_e64 v131, v132, v133, s[40:41]
	v_mul_f32_e32 v132, 0x37800000, v131
	v_cndmask_b32_e32 v131, v131, v132, vcc
	v_cmp_class_f32_e32 vcc, v130, v241
	s_nop 1
	v_cndmask_b32_e32 v137, v131, v130, vcc
	v_ashrrev_i32_e32 v130, 8, v162
	v_and_b32_e32 v140, -8, v130
	v_add_u32_e32 v130, s1, v140
	v_lshl_or_b32 v132, v130, 5, v141
	v_div_scale_f32 v130, s[10:11], v163, v163, 1.0
	v_rcp_f32_e32 v131, v130
	v_ashrrev_i32_e32 v133, 31, v132
	v_fma_f32 v134, -v130, v131, 1.0
	v_fmac_f32_e32 v131, v134, v131
	v_div_scale_f32 v134, vcc, 1.0, v163, 1.0
	v_mul_f32_e32 v135, v134, v131
	v_fma_f32 v136, -v130, v135, v134
	v_fmac_f32_e32 v135, v136, v131
	v_fma_f32 v130, -v130, v135, v134
	v_div_fmas_f32 v130, v130, v131, v135
	v_div_scale_f32 v131, s[10:11], v164, v164, 1.0
	v_rcp_f32_e32 v134, v131
	v_div_fixup_f32 v130, v130, v163, 1.0
	v_fma_f32 v135, -v131, v134, 1.0
	v_fmac_f32_e32 v134, v135, v134
	v_div_scale_f32 v135, vcc, 1.0, v164, 1.0
	v_mul_f32_e32 v136, v135, v134
	v_fma_f32 v138, -v131, v136, v135
	v_fmac_f32_e32 v136, v138, v134
	v_fma_f32 v131, -v131, v136, v135
	v_div_fmas_f32 v131, v131, v134, v136
	v_div_fixup_f32 v131, v131, v164, 1.0
	v_pk_mul_f32 v[126:127], v[126:127], v[130:131]
	v_pk_mul_f32 v[110:111], v[110:111], v[130:131]
	v_cvt_pk_bf16_f32 v134, v126, v127
	v_div_scale_f32 v126, s[10:11], v166, v166, 1.0
	v_rcp_f32_e32 v127, v126
	v_pk_mul_f32 v[102:103], v[102:103], v[130:131]
	v_cvt_pk_bf16_f32 v110, v110, v111
	v_cvt_pk_bf16_f32 v102, v102, v103
	v_fma_f32 v135, -v126, v127, 1.0
	v_fmac_f32_e32 v127, v135, v127
	v_div_scale_f32 v135, vcc, 1.0, v166, 1.0
	v_mul_f32_e32 v136, v135, v127
	v_fma_f32 v138, -v126, v136, v135
	v_fmac_f32_e32 v136, v138, v127
	v_fma_f32 v126, -v126, v136, v135
	v_div_fmas_f32 v126, v126, v127, v136
	v_div_fixup_f32 v127, v126, v166, 1.0
	v_div_scale_f32 v126, s[10:11], v165, v165, 1.0
	v_rcp_f32_e32 v135, v126
	v_pk_mul_f32 v[118:119], v[118:119], v[130:131]
	v_pk_mul_f32 v[94:95], v[94:95], v[130:131]
	v_cvt_pk_bf16_f32 v118, v118, v119
	v_fma_f32 v136, -v126, v135, 1.0
	v_fmac_f32_e32 v135, v136, v135
	v_div_scale_f32 v136, vcc, 1.0, v165, 1.0
	v_mul_f32_e32 v138, v136, v135
	v_fma_f32 v139, -v126, v138, v136
	v_fmac_f32_e32 v138, v139, v135
	v_fma_f32 v126, -v126, v138, v136
	v_div_fmas_f32 v126, v126, v135, v138
	v_div_fixup_f32 v126, v126, v165, 1.0
	v_pk_mul_f32 v[128:129], v[128:129], v[126:127]
	v_pk_mul_f32 v[112:113], v[112:113], v[126:127]
	v_cvt_pk_bf16_f32 v135, v128, v129
	v_div_scale_f32 v128, s[10:11], v168, v168, 1.0
	v_rcp_f32_e32 v129, v128
	v_pk_mul_f32 v[104:105], v[104:105], v[126:127]
	v_cvt_pk_bf16_f32 v111, v112, v113
	v_cvt_pk_bf16_f32 v103, v104, v105
	v_fma_f32 v136, -v128, v129, 1.0
	v_fmac_f32_e32 v129, v136, v129
	v_div_scale_f32 v136, vcc, 1.0, v168, 1.0
	v_mul_f32_e32 v138, v136, v129
	v_fma_f32 v139, -v128, v138, v136
	v_fmac_f32_e32 v138, v139, v129
	v_fma_f32 v128, -v128, v138, v136
	v_div_fmas_f32 v128, v128, v129, v138
	v_div_fixup_f32 v129, v128, v168, 1.0
	v_div_scale_f32 v128, s[10:11], v167, v167, 1.0
	v_rcp_f32_e32 v136, v128
	v_pk_mul_f32 v[120:121], v[120:121], v[126:127]
	v_pk_mul_f32 v[96:97], v[96:97], v[126:127]
	v_cvt_pk_bf16_f32 v119, v120, v121
	v_fma_f32 v138, -v128, v136, 1.0
	v_fmac_f32_e32 v136, v138, v136
	v_div_scale_f32 v138, vcc, 1.0, v167, 1.0
	v_mul_f32_e32 v139, v138, v136
	v_fma_f32 v143, -v128, v139, v138
	v_fmac_f32_e32 v139, v143, v136
	v_fma_f32 v128, -v128, v139, v138
	v_div_fmas_f32 v128, v128, v136, v139
	v_div_fixup_f32 v128, v128, v167, 1.0
	v_pk_mul_f32 v[122:123], v[122:123], v[128:129]
	v_pk_mul_f32 v[106:107], v[106:107], v[128:129]
	v_cvt_pk_bf16_f32 v136, v122, v123
	v_div_scale_f32 v122, s[10:11], v137, v137, 1.0
	v_rcp_f32_e32 v123, v122
	v_pk_mul_f32 v[98:99], v[98:99], v[128:129]
	v_cvt_pk_bf16_f32 v112, v106, v107
	v_cvt_pk_bf16_f32 v104, v98, v99
	v_fma_f32 v138, -v122, v123, 1.0
	v_fmac_f32_e32 v123, v138, v123
	v_div_scale_f32 v138, vcc, 1.0, v137, 1.0
	v_mul_f32_e32 v139, v138, v123
	v_fma_f32 v143, -v122, v139, v138
	v_fmac_f32_e32 v139, v143, v123
	v_fma_f32 v122, -v122, v139, v138
	v_div_fmas_f32 v122, v122, v123, v139
	v_div_fixup_f32 v139, v122, v137, 1.0
	v_div_scale_f32 v122, s[10:11], v169, v169, 1.0
	v_rcp_f32_e32 v123, v122
	v_pk_mul_f32 v[114:115], v[114:115], v[128:129]
	v_pk_mul_f32 v[90:91], v[90:91], v[128:129]
	v_cvt_pk_bf16_f32 v114, v114, v115
	v_fma_f32 v137, -v122, v123, 1.0
	v_fmac_f32_e32 v123, v137, v123
	v_div_scale_f32 v137, vcc, 1.0, v169, 1.0
	v_mul_f32_e32 v138, v137, v123
	v_fma_f32 v143, -v122, v138, v137
	v_fmac_f32_e32 v138, v143, v123
	v_fma_f32 v122, -v122, v138, v137
	v_div_fmas_f32 v122, v122, v123, v138
	v_div_fixup_f32 v138, v122, v169, 1.0
	v_pk_mul_f32 v[122:123], v[124:125], v[138:139]
	v_pk_mul_f32 v[106:107], v[108:109], v[138:139]
	v_cvt_pk_bf16_f32 v137, v122, v123
	v_lshlrev_b64 v[122:123], 14, v[132:133]
	v_pk_mul_f32 v[98:99], v[100:101], v[138:139]
	v_lshl_add_u64 v[124:125], s[12:13], 0, v[122:123]
	v_cvt_pk_bf16_f32 v113, v106, v107
	v_or_b32_e32 v106, 0x1000, v0
	v_mov_b32_e32 v107, v1
	v_cvt_pk_bf16_f32 v105, v98, v99
	v_or_b32_e32 v98, 0x1800, v0
	v_mov_b32_e32 v99, v1
	v_lshl_add_u64 v[132:133], v[124:125], 0, v[0:1]
	v_lshlrev_b32_e32 v122, 1, v142
	v_mov_b32_e32 v123, v1
	v_lshl_add_u64 v[108:109], v[124:125], 0, v[106:107]
	v_lshl_add_u64 v[100:101], v[124:125], 0, v[98:99]
	v_lshl_add_u64 v[132:133], v[132:133], 0, v[122:123]
	v_pk_mul_f32 v[116:117], v[116:117], v[138:139]
	v_lshl_add_u64 v[108:109], v[108:109], 0, v[122:123]
	v_lshl_add_u64 v[100:101], v[100:101], 0, v[122:123]
	global_store_dwordx2 v[132:133], v[134:135], off
	global_store_dwordx2 v[132:133], v[136:137], off offset:16
	v_cvt_pk_bf16_f32 v115, v116, v117
	global_store_dwordx2 v[132:133], v[118:119], off offset:2048
	global_store_dwordx2 v[132:133], v[114:115], off offset:2064
	global_store_dwordx2 v[108:109], v[110:111], off
	global_store_dwordx2 v[108:109], v[112:113], off offset:16
	global_store_dwordx2 v[100:101], v[102:103], off
	global_store_dwordx2 v[100:101], v[104:105], off offset:16
	v_add_u32_e32 v100, s5, v140
	v_lshl_or_b32 v100, v100, 5, v141
	v_ashrrev_i32_e32 v101, 31, v100
	v_pk_mul_f32 v[92:93], v[92:93], v[138:139]
	v_cvt_pk_bf16_f32 v90, v90, v91
	v_cvt_pk_bf16_f32 v91, v92, v93
	v_lshlrev_b64 v[92:93], 14, v[100:101]
	v_lshl_add_u64 v[92:93], s[12:13], 0, v[92:93]
	v_pk_mul_f32 v[74:75], v[74:75], v[128:129]
	v_pk_mul_f32 v[76:77], v[76:77], v[138:139]
	v_pk_mul_f32 v[66:67], v[66:67], v[128:129]
	v_pk_mul_f32 v[68:69], v[68:69], v[138:139]
	v_cvt_pk_bf16_f32 v94, v94, v95
	v_cvt_pk_bf16_f32 v95, v96, v97
	v_lshl_add_u64 v[96:97], v[92:93], 0, v[0:1]
	v_pk_mul_f32 v[86:87], v[86:87], v[130:131]
	v_pk_mul_f32 v[88:89], v[88:89], v[126:127]
	v_pk_mul_f32 v[78:79], v[78:79], v[130:131]
	v_pk_mul_f32 v[80:81], v[80:81], v[126:127]
	v_cvt_pk_bf16_f32 v74, v74, v75
	v_cvt_pk_bf16_f32 v75, v76, v77
	v_lshl_add_u64 v[76:77], v[92:93], 0, v[106:107]
	v_pk_mul_f32 v[70:71], v[70:71], v[130:131]
	v_pk_mul_f32 v[72:73], v[72:73], v[126:127]
	v_cvt_pk_bf16_f32 v66, v66, v67
	v_cvt_pk_bf16_f32 v67, v68, v69
	v_lshl_add_u64 v[68:69], v[92:93], 0, v[98:99]
	v_lshl_add_u64 v[96:97], v[96:97], 0, v[122:123]
	v_cvt_pk_bf16_f32 v86, v86, v87
	v_cvt_pk_bf16_f32 v87, v88, v89
	v_pk_mul_f32 v[82:83], v[82:83], v[128:129]
	v_pk_mul_f32 v[84:85], v[84:85], v[138:139]
	v_cvt_pk_bf16_f32 v78, v78, v79
	v_cvt_pk_bf16_f32 v79, v80, v81
	v_lshl_add_u64 v[76:77], v[76:77], 0, v[122:123]
	v_cvt_pk_bf16_f32 v70, v70, v71
	v_cvt_pk_bf16_f32 v71, v72, v73
	v_lshl_add_u64 v[68:69], v[68:69], 0, v[122:123]
	global_store_dwordx2 v[96:97], v[94:95], off
	global_store_dwordx2 v[96:97], v[90:91], off offset:16
	v_cvt_pk_bf16_f32 v82, v82, v83
	v_cvt_pk_bf16_f32 v83, v84, v85
	global_store_dwordx2 v[96:97], v[86:87], off offset:2048
	global_store_dwordx2 v[96:97], v[82:83], off offset:2064
	global_store_dwordx2 v[76:77], v[78:79], off
	global_store_dwordx2 v[76:77], v[74:75], off offset:16
	global_store_dwordx2 v[68:69], v[70:71], off
	global_store_dwordx2 v[68:69], v[66:67], off offset:16
	v_add_co_u32_e32 v66, vcc, s3, v158
	v_lshl_add_u64 v[80:81], v[158:159], 0, s[90:91]
	s_nop 0
	v_addc_co_u32_e32 v67, vcc, 0, v159, vcc
	global_load_dwordx4 v[68:71], v[66:67], off
	global_load_dwordx4 v[72:75], v[80:81], off offset:16
	global_load_dwordx4 v[76:79], v[80:81], off offset:48
	s_nop 0
	global_load_dwordx4 v[80:83], v[80:81], off offset:32
	s_mov_b64 s[10:11], 0x2040
	s_waitcnt vmcnt(3)
	v_mov_b32_e32 v84, v68
	s_waitcnt vmcnt(0)
	v_mov_b32_e32 v85, v80
	v_mov_b32_e32 v80, v69
	v_pk_add_f32 v[68:69], v[84:85], v[80:81]
	v_mov_b32_e32 v80, v70
	v_mov_b32_e32 v81, v82
	v_mov_b32_e32 v82, v71
	v_pk_add_f32 v[70:71], v[80:81], v[82:83]
	v_lshl_add_u64 v[80:81], v[158:159], 0, s[10:11]
	v_pk_add_f32 v[68:69], v[68:69], v[70:71]
	v_mov_b32_e32 v70, v72
	v_mov_b32_e32 v71, v76
	v_mov_b32_e32 v76, v73
	v_mov_b32_e32 v72, v74
	v_mov_b32_e32 v73, v78
	v_mov_b32_e32 v78, v75
	v_pk_add_f32 v[70:71], v[70:71], v[76:77]
	v_pk_add_f32 v[72:73], v[72:73], v[78:79]
	s_mov_b64 s[10:11], 0x2080
	v_pk_add_f32 v[70:71], v[70:71], v[72:73]
	s_nop 0
	v_pk_add_f32 v[68:69], v[68:69], v[70:71]
	s_nop 0
	v_add_f32_e32 v68, v68, v69
	v_fmamk_f32 v68, v68, 0x3a800000, v240
	v_cmp_gt_f32_e32 vcc, s31, v68
	v_mul_f32_e32 v69, 0x4f800000, v68
	s_nop 0
	v_cndmask_b32_e32 v68, v68, v69, vcc
	v_sqrt_f32_e32 v69, v68
	s_nop 0
	v_add_u32_e32 v70, -1, v69
	v_fma_f32 v71, -v70, v69, v68
	v_cmp_ge_f32_e64 s[40:41], 0, v71
	v_add_u32_e32 v71, 1, v69
	s_nop 0
	v_cndmask_b32_e64 v70, v69, v70, s[40:41]
	v_fma_f32 v69, -v71, v69, v68
	v_cmp_lt_f32_e64 s[40:41], 0, v69
	s_nop 1
	v_cndmask_b32_e64 v69, v70, v71, s[40:41]
	v_mul_f32_e32 v70, 0x37800000, v69
	v_cndmask_b32_e32 v69, v69, v70, vcc
	v_cmp_class_f32_e32 vcc, v68, v241
	s_nop 1
	v_cndmask_b32_e32 v82, v69, v68, vcc
	global_load_dwordx4 v[68:71], v[66:67], off offset:64
	global_load_dwordx4 v[72:75], v[80:81], off offset:16
	global_load_dwordx4 v[76:79], v[80:81], off offset:48
	global_load_dwordx4 v[84:87], v[80:81], off offset:32
	s_waitcnt vmcnt(3)
	v_mov_b32_e32 v80, v68
	s_waitcnt vmcnt(0)
	v_mov_b32_e32 v81, v84
	v_mov_b32_e32 v84, v69
	v_pk_add_f32 v[68:69], v[80:81], v[84:85]
	v_mov_b32_e32 v80, v70
	v_mov_b32_e32 v81, v86
	v_mov_b32_e32 v86, v71
	v_pk_add_f32 v[70:71], v[80:81], v[86:87]
	v_lshl_add_u64 v[80:81], v[158:159], 0, s[10:11]
	v_pk_add_f32 v[68:69], v[68:69], v[70:71]
	v_mov_b32_e32 v70, v72
	v_mov_b32_e32 v71, v76
	v_mov_b32_e32 v76, v73
	v_mov_b32_e32 v72, v74
	v_mov_b32_e32 v73, v78
	v_mov_b32_e32 v78, v75
	v_pk_add_f32 v[70:71], v[70:71], v[76:77]
	v_pk_add_f32 v[72:73], v[72:73], v[78:79]
	s_mov_b64 s[10:11], 0x20c0
	v_pk_add_f32 v[70:71], v[70:71], v[72:73]
	s_nop 0
	v_pk_add_f32 v[68:69], v[68:69], v[70:71]
	s_nop 0
	v_add_f32_e32 v68, v68, v69
	v_fmamk_f32 v68, v68, 0x3a800000, v240
	v_cmp_gt_f32_e32 vcc, s31, v68
	v_mul_f32_e32 v69, 0x4f800000, v68
	s_nop 0
	v_cndmask_b32_e32 v68, v68, v69, vcc
	v_sqrt_f32_e32 v69, v68
	s_nop 0
	v_add_u32_e32 v70, -1, v69
	v_fma_f32 v71, -v70, v69, v68
	v_cmp_ge_f32_e64 s[40:41], 0, v71
	v_add_u32_e32 v71, 1, v69
	s_nop 0
	v_cndmask_b32_e64 v70, v69, v70, s[40:41]
	v_fma_f32 v69, -v71, v69, v68
	v_cmp_lt_f32_e64 s[40:41], 0, v69
	s_nop 1
	v_cndmask_b32_e64 v69, v70, v71, s[40:41]
	v_mul_f32_e32 v70, 0x37800000, v69
	v_cndmask_b32_e32 v69, v69, v70, vcc
	v_cmp_class_f32_e32 vcc, v68, v241
	s_nop 1
	v_cndmask_b32_e32 v83, v69, v68, vcc
	global_load_dwordx4 v[68:71], v[66:67], off offset:128
	global_load_dwordx4 v[72:75], v[80:81], off offset:16
	global_load_dwordx4 v[76:79], v[80:81], off offset:48
	global_load_dwordx4 v[84:87], v[80:81], off offset:32
	s_waitcnt vmcnt(3)
	v_mov_b32_e32 v80, v68
	s_waitcnt vmcnt(0)
	v_mov_b32_e32 v81, v84
	v_mov_b32_e32 v84, v69
	v_pk_add_f32 v[68:69], v[80:81], v[84:85]
	v_mov_b32_e32 v80, v70
	v_mov_b32_e32 v81, v86
	v_mov_b32_e32 v86, v71
	v_pk_add_f32 v[70:71], v[80:81], v[86:87]
	v_lshl_add_u64 v[80:81], v[158:159], 0, s[10:11]
	v_pk_add_f32 v[68:69], v[68:69], v[70:71]
	v_mov_b32_e32 v70, v72
	v_mov_b32_e32 v71, v76
	v_mov_b32_e32 v76, v73
	v_mov_b32_e32 v72, v74
	v_mov_b32_e32 v73, v78
	v_mov_b32_e32 v78, v75
	v_pk_add_f32 v[70:71], v[70:71], v[76:77]
	v_pk_add_f32 v[72:73], v[72:73], v[78:79]
	s_mov_b64 s[10:11], 0x2100
	v_pk_add_f32 v[70:71], v[70:71], v[72:73]
	s_nop 0
	v_pk_add_f32 v[68:69], v[68:69], v[70:71]
	s_nop 0
	v_add_f32_e32 v68, v68, v69
	v_fmamk_f32 v68, v68, 0x3a800000, v240
	v_cmp_gt_f32_e32 vcc, s31, v68
	v_mul_f32_e32 v69, 0x4f800000, v68
	s_nop 0
	v_cndmask_b32_e32 v68, v68, v69, vcc
	v_sqrt_f32_e32 v69, v68
	s_nop 0
	v_add_u32_e32 v70, -1, v69
	v_fma_f32 v71, -v70, v69, v68
	v_cmp_ge_f32_e64 s[40:41], 0, v71
	v_add_u32_e32 v71, 1, v69
	s_nop 0
	v_cndmask_b32_e64 v70, v69, v70, s[40:41]
	v_fma_f32 v69, -v71, v69, v68
	v_cmp_lt_f32_e64 s[40:41], 0, v69
	s_nop 1
	v_cndmask_b32_e64 v69, v70, v71, s[40:41]
	v_mul_f32_e32 v70, 0x37800000, v69
	v_cndmask_b32_e32 v69, v69, v70, vcc
	v_cmp_class_f32_e32 vcc, v68, v241
	s_nop 1
	v_cndmask_b32_e32 v84, v69, v68, vcc
	global_load_dwordx4 v[68:71], v[66:67], off offset:192
	global_load_dwordx4 v[72:75], v[80:81], off offset:16
	global_load_dwordx4 v[76:79], v[80:81], off offset:48
	global_load_dwordx4 v[86:89], v[80:81], off offset:32
	s_waitcnt vmcnt(3)
	v_mov_b32_e32 v80, v68
	s_waitcnt vmcnt(0)
	v_mov_b32_e32 v81, v86
	v_mov_b32_e32 v86, v69
	v_pk_add_f32 v[68:69], v[80:81], v[86:87]
	v_mov_b32_e32 v80, v70
	v_mov_b32_e32 v81, v88
	v_mov_b32_e32 v88, v71
	v_pk_add_f32 v[70:71], v[80:81], v[88:89]
	v_lshl_add_u64 v[80:81], v[158:159], 0, s[10:11]
	v_pk_add_f32 v[68:69], v[68:69], v[70:71]
	v_mov_b32_e32 v70, v72
	v_mov_b32_e32 v71, v76
	v_mov_b32_e32 v76, v73
	v_mov_b32_e32 v72, v74
	v_mov_b32_e32 v73, v78
	v_mov_b32_e32 v78, v75
	v_pk_add_f32 v[70:71], v[70:71], v[76:77]
	v_pk_add_f32 v[72:73], v[72:73], v[78:79]
	s_mov_b64 s[10:11], 0x2140
	v_pk_add_f32 v[70:71], v[70:71], v[72:73]
	s_nop 0
	v_pk_add_f32 v[68:69], v[68:69], v[70:71]
	s_nop 0
	v_add_f32_e32 v68, v68, v69
	v_fmamk_f32 v68, v68, 0x3a800000, v240
	v_cmp_gt_f32_e32 vcc, s31, v68
	v_mul_f32_e32 v69, 0x4f800000, v68
	s_nop 0
	v_cndmask_b32_e32 v68, v68, v69, vcc
	v_sqrt_f32_e32 v69, v68
	s_nop 0
	v_add_u32_e32 v70, -1, v69
	v_fma_f32 v71, -v70, v69, v68
	v_cmp_ge_f32_e64 s[40:41], 0, v71
	v_add_u32_e32 v71, 1, v69
	s_nop 0
	v_cndmask_b32_e64 v70, v69, v70, s[40:41]
	v_fma_f32 v69, -v71, v69, v68
	v_cmp_lt_f32_e64 s[40:41], 0, v69
	s_nop 1
	v_cndmask_b32_e64 v69, v70, v71, s[40:41]
	v_mul_f32_e32 v70, 0x37800000, v69
	v_cndmask_b32_e32 v69, v69, v70, vcc
	v_cmp_class_f32_e32 vcc, v68, v241
	s_nop 1
	v_cndmask_b32_e32 v87, v69, v68, vcc
	global_load_dwordx4 v[68:71], v[66:67], off offset:256
	global_load_dwordx4 v[72:75], v[80:81], off offset:16
	global_load_dwordx4 v[76:79], v[80:81], off offset:48
	global_load_dwordx4 v[88:91], v[80:81], off offset:32
	s_waitcnt vmcnt(3)
	v_mov_b32_e32 v80, v68
	s_waitcnt vmcnt(0)
	v_mov_b32_e32 v81, v88
	v_mov_b32_e32 v88, v69
	v_pk_add_f32 v[68:69], v[80:81], v[88:89]
	v_mov_b32_e32 v80, v70
	v_mov_b32_e32 v81, v90
	v_mov_b32_e32 v90, v71
	v_pk_add_f32 v[70:71], v[80:81], v[90:91]
	v_lshl_add_u64 v[80:81], v[158:159], 0, s[10:11]
	v_pk_add_f32 v[68:69], v[68:69], v[70:71]
	v_mov_b32_e32 v70, v72
	v_mov_b32_e32 v71, v76
	v_mov_b32_e32 v76, v73
	v_mov_b32_e32 v72, v74
	v_mov_b32_e32 v73, v78
	v_mov_b32_e32 v78, v75
	v_pk_add_f32 v[70:71], v[70:71], v[76:77]
	v_pk_add_f32 v[72:73], v[72:73], v[78:79]
	s_mov_b64 s[10:11], 0x2180
	v_pk_add_f32 v[70:71], v[70:71], v[72:73]
	s_nop 0
	v_pk_add_f32 v[68:69], v[68:69], v[70:71]
	s_nop 0
	v_add_f32_e32 v68, v68, v69
	v_fmamk_f32 v68, v68, 0x3a800000, v240
	v_cmp_gt_f32_e32 vcc, s31, v68
	v_mul_f32_e32 v69, 0x4f800000, v68
	s_nop 0
	v_cndmask_b32_e32 v68, v68, v69, vcc
	v_sqrt_f32_e32 v69, v68
	s_nop 0
	v_add_u32_e32 v70, -1, v69
	v_fma_f32 v71, -v70, v69, v68
	v_cmp_ge_f32_e64 s[40:41], 0, v71
	v_add_u32_e32 v71, 1, v69
	s_nop 0
	v_cndmask_b32_e64 v70, v69, v70, s[40:41]
	v_fma_f32 v69, -v71, v69, v68
	v_cmp_lt_f32_e64 s[40:41], 0, v69
	s_nop 1
	v_cndmask_b32_e64 v69, v70, v71, s[40:41]
	v_mul_f32_e32 v70, 0x37800000, v69
	v_cndmask_b32_e32 v69, v69, v70, vcc
	v_cmp_class_f32_e32 vcc, v68, v241
	s_nop 1
	v_cndmask_b32_e32 v85, v69, v68, vcc
	global_load_dwordx4 v[68:71], v[66:67], off offset:320
	global_load_dwordx4 v[72:75], v[80:81], off offset:16
	global_load_dwordx4 v[76:79], v[80:81], off offset:48
	global_load_dwordx4 v[88:91], v[80:81], off offset:32
	s_waitcnt vmcnt(3)
	v_mov_b32_e32 v80, v68
	s_waitcnt vmcnt(0)
	v_mov_b32_e32 v81, v88
	v_mov_b32_e32 v88, v69
	v_pk_add_f32 v[68:69], v[80:81], v[88:89]
	v_mov_b32_e32 v80, v70
	v_mov_b32_e32 v81, v90
	v_mov_b32_e32 v90, v71
	v_pk_add_f32 v[70:71], v[80:81], v[90:91]
	v_lshl_add_u64 v[80:81], v[158:159], 0, s[10:11]
	v_pk_add_f32 v[68:69], v[68:69], v[70:71]
	v_mov_b32_e32 v70, v72
	v_mov_b32_e32 v71, v76
	v_mov_b32_e32 v76, v73
	v_mov_b32_e32 v72, v74
	v_mov_b32_e32 v73, v78
	v_mov_b32_e32 v78, v75
	v_pk_add_f32 v[70:71], v[70:71], v[76:77]
	v_pk_add_f32 v[72:73], v[72:73], v[78:79]
	s_mov_b64 s[10:11], 0x21c0
	v_pk_add_f32 v[70:71], v[70:71], v[72:73]
	s_nop 0
	v_pk_add_f32 v[68:69], v[68:69], v[70:71]
	s_nop 0
	v_add_f32_e32 v68, v68, v69
	v_fmamk_f32 v68, v68, 0x3a800000, v240
	v_cmp_gt_f32_e32 vcc, s31, v68
	v_mul_f32_e32 v69, 0x4f800000, v68
	s_nop 0
	v_cndmask_b32_e32 v68, v68, v69, vcc
	v_sqrt_f32_e32 v69, v68
	s_nop 0
	v_add_u32_e32 v70, -1, v69
	v_fma_f32 v71, -v70, v69, v68
	v_cmp_ge_f32_e64 s[40:41], 0, v71
	v_add_u32_e32 v71, 1, v69
	s_nop 0
	v_cndmask_b32_e64 v70, v69, v70, s[40:41]
	v_fma_f32 v69, -v71, v69, v68
	v_cmp_lt_f32_e64 s[40:41], 0, v69
	s_nop 1
	v_cndmask_b32_e64 v69, v70, v71, s[40:41]
	v_mul_f32_e32 v70, 0x37800000, v69
	v_cndmask_b32_e32 v69, v69, v70, vcc
	v_cmp_class_f32_e32 vcc, v68, v241
	s_nop 1
	v_cndmask_b32_e32 v88, v69, v68, vcc
	global_load_dwordx4 v[68:71], v[66:67], off offset:384
	global_load_dwordx4 v[72:75], v[80:81], off offset:16
	global_load_dwordx4 v[76:79], v[80:81], off offset:48
	global_load_dwordx4 v[90:93], v[80:81], off offset:32
	s_waitcnt vmcnt(3)
	v_mov_b32_e32 v80, v68
	s_waitcnt vmcnt(0)
	v_mov_b32_e32 v81, v90
	v_mov_b32_e32 v90, v69
	v_pk_add_f32 v[68:69], v[80:81], v[90:91]
	v_mov_b32_e32 v80, v70
	v_mov_b32_e32 v81, v92
	v_mov_b32_e32 v92, v71
	v_pk_add_f32 v[70:71], v[80:81], v[92:93]
	s_nop 0
	v_pk_add_f32 v[68:69], v[68:69], v[70:71]
	v_mov_b32_e32 v70, v72
	v_mov_b32_e32 v71, v76
	v_mov_b32_e32 v76, v73
	v_mov_b32_e32 v72, v74
	v_mov_b32_e32 v73, v78
	v_mov_b32_e32 v78, v75
	v_pk_add_f32 v[70:71], v[70:71], v[76:77]
	v_pk_add_f32 v[72:73], v[72:73], v[78:79]
	v_lshl_add_u64 v[78:79], v[158:159], 0, s[10:11]
	v_pk_add_f32 v[70:71], v[70:71], v[72:73]
	s_nop 0
	v_pk_add_f32 v[68:69], v[68:69], v[70:71]
	s_nop 0
	v_add_f32_e32 v68, v68, v69
	v_fmamk_f32 v68, v68, 0x3a800000, v240
	v_cmp_gt_f32_e32 vcc, s31, v68
	v_mul_f32_e32 v69, 0x4f800000, v68
	s_nop 0
	v_cndmask_b32_e32 v68, v68, v69, vcc
	v_sqrt_f32_e32 v69, v68
	s_nop 0
	v_add_u32_e32 v70, -1, v69
	v_fma_f32 v71, -v70, v69, v68
	v_cmp_ge_f32_e64 s[40:41], 0, v71
	v_add_u32_e32 v71, 1, v69
	s_nop 0
	v_cndmask_b32_e64 v70, v69, v70, s[40:41]
	v_fma_f32 v69, -v71, v69, v68
	v_cmp_lt_f32_e64 s[40:41], 0, v69
	s_nop 1
	v_cndmask_b32_e64 v69, v70, v71, s[40:41]
	v_mul_f32_e32 v70, 0x37800000, v69
	v_cndmask_b32_e32 v69, v69, v70, vcc
	v_cmp_class_f32_e32 vcc, v68, v241
	s_nop 1
	v_cndmask_b32_e32 v86, v69, v68, vcc
	global_load_dwordx4 v[70:73], v[66:67], off offset:448
	s_nop 0
	global_load_dwordx4 v[66:69], v[78:79], off offset:16
	global_load_dwordx4 v[74:77], v[78:79], off offset:48
	s_nop 0
	global_load_dwordx4 v[78:81], v[78:79], off offset:32
	s_waitcnt vmcnt(3)
	v_mov_b32_e32 v90, v70
	s_waitcnt vmcnt(0)
	v_mov_b32_e32 v91, v78
	v_mov_b32_e32 v78, v71
	v_pk_add_f32 v[70:71], v[90:91], v[78:79]
	v_mov_b32_e32 v78, v72
	v_mov_b32_e32 v79, v80
	v_mov_b32_e32 v80, v73
	v_pk_add_f32 v[72:73], v[78:79], v[80:81]
	s_nop 0
	v_pk_add_f32 v[70:71], v[70:71], v[72:73]
	v_mov_b32_e32 v72, v66
	v_mov_b32_e32 v73, v74
	v_mov_b32_e32 v74, v67
	v_pk_add_f32 v[66:67], v[72:73], v[74:75]
	v_mov_b32_e32 v72, v68
	v_mov_b32_e32 v73, v76
	v_mov_b32_e32 v76, v69
	v_pk_add_f32 v[68:69], v[72:73], v[76:77]
	s_nop 0
	v_pk_add_f32 v[66:67], v[66:67], v[68:69]
	s_nop 0
	v_pk_add_f32 v[66:67], v[70:71], v[66:67]
	s_nop 0
	v_add_f32_e32 v66, v66, v67
	v_fmamk_f32 v66, v66, 0x3a800000, v240
	v_cmp_gt_f32_e32 vcc, s31, v66
	v_mul_f32_e32 v67, 0x4f800000, v66
	s_nop 0
	v_cndmask_b32_e32 v66, v66, v67, vcc
	v_sqrt_f32_e32 v67, v66
	s_nop 0
	v_add_u32_e32 v68, -1, v67
	v_fma_f32 v69, -v68, v67, v66
	v_cmp_ge_f32_e64 s[40:41], 0, v69
	v_add_u32_e32 v69, 1, v67
	s_nop 0
	v_cndmask_b32_e64 v68, v67, v68, s[40:41]
	v_fma_f32 v67, -v69, v67, v66
	v_cmp_lt_f32_e64 s[40:41], 0, v67
	s_nop 1
	v_cndmask_b32_e64 v67, v68, v69, s[40:41]
	v_mul_f32_e32 v68, 0x37800000, v67
	v_cndmask_b32_e32 v67, v67, v68, vcc
	v_cmp_class_f32_e32 vcc, v66, v241
	s_nop 1
	v_cndmask_b32_e32 v72, v67, v66, vcc
	v_add_u32_e32 v66, 0x80, v162
	v_ashrrev_i32_e32 v67, 8, v66
	v_and_b32_e32 v74, -8, v67
	v_bfe_u32 v75, v66, 6, 5
	v_add_u32_e32 v66, s1, v74
	v_lshl_or_b32 v68, v66, 5, v75
	v_div_scale_f32 v66, s[10:11], v83, v83, 1.0
	v_rcp_f32_e32 v67, v66
	v_ashrrev_i32_e32 v69, 31, v68
	v_fma_f32 v70, -v66, v67, 1.0
	v_fmac_f32_e32 v67, v70, v67
	v_div_scale_f32 v70, vcc, 1.0, v83, 1.0
	v_mul_f32_e32 v71, v70, v67
	v_fma_f32 v73, -v66, v71, v70
	v_fmac_f32_e32 v71, v73, v67
	v_fma_f32 v66, -v66, v71, v70
	v_div_fmas_f32 v66, v66, v67, v71
	v_div_fixup_f32 v67, v66, v83, 1.0
	v_div_scale_f32 v66, s[10:11], v82, v82, 1.0
	v_rcp_f32_e32 v70, v66
	s_nop 0
	v_fma_f32 v71, -v66, v70, 1.0
	v_fmac_f32_e32 v70, v71, v70
	v_div_scale_f32 v71, vcc, 1.0, v82, 1.0
	v_mul_f32_e32 v73, v71, v70
	v_fma_f32 v76, -v66, v73, v71
	v_fmac_f32_e32 v73, v76, v70
	v_fma_f32 v66, -v66, v73, v71
	v_div_fmas_f32 v66, v66, v70, v73
	v_div_fixup_f32 v66, v66, v82, 1.0
	v_pk_mul_f32 v[62:63], v[62:63], v[66:67]
	v_pk_mul_f32 v[54:55], v[54:55], v[66:67]
	v_cvt_pk_bf16_f32 v70, v62, v63
	v_div_scale_f32 v62, s[10:11], v87, v87, 1.0
	v_rcp_f32_e32 v63, v62
	v_pk_mul_f32 v[46:47], v[46:47], v[66:67]
	v_pk_mul_f32 v[38:39], v[38:39], v[66:67]
	v_cvt_pk_bf16_f32 v54, v54, v55
	v_fma_f32 v71, -v62, v63, 1.0
	v_fmac_f32_e32 v63, v71, v63
	v_div_scale_f32 v71, vcc, 1.0, v87, 1.0
	v_mul_f32_e32 v73, v71, v63
	v_fma_f32 v76, -v62, v73, v71
	v_fmac_f32_e32 v73, v76, v63
	v_fma_f32 v62, -v62, v73, v71
	v_div_fmas_f32 v62, v62, v63, v73
	v_div_fixup_f32 v63, v62, v87, 1.0
	v_div_scale_f32 v62, s[10:11], v84, v84, 1.0
	v_rcp_f32_e32 v71, v62
	v_cvt_pk_bf16_f32 v46, v46, v47
	v_cvt_pk_bf16_f32 v38, v38, v39
	v_pk_mul_f32 v[30:31], v[30:31], v[66:67]
	v_fma_f32 v73, -v62, v71, 1.0
	v_fmac_f32_e32 v71, v73, v71
	v_div_scale_f32 v73, vcc, 1.0, v84, 1.0
	v_mul_f32_e32 v76, v73, v71
	v_fma_f32 v77, -v62, v76, v73
	v_fmac_f32_e32 v76, v77, v71
	v_fma_f32 v62, -v62, v76, v73
	v_div_fmas_f32 v62, v62, v71, v76
	v_div_fixup_f32 v62, v62, v84, 1.0
	v_pk_mul_f32 v[64:65], v[64:65], v[62:63]
	v_pk_mul_f32 v[56:57], v[56:57], v[62:63]
	v_cvt_pk_bf16_f32 v71, v64, v65
	v_div_scale_f32 v64, s[10:11], v88, v88, 1.0
	v_rcp_f32_e32 v65, v64
	v_pk_mul_f32 v[48:49], v[48:49], v[62:63]
	v_pk_mul_f32 v[40:41], v[40:41], v[62:63]
	v_cvt_pk_bf16_f32 v55, v56, v57
	v_fma_f32 v73, -v64, v65, 1.0
	v_fmac_f32_e32 v65, v73, v65
	v_div_scale_f32 v73, vcc, 1.0, v88, 1.0
	v_mul_f32_e32 v76, v73, v65
	v_fma_f32 v77, -v64, v76, v73
	v_fmac_f32_e32 v76, v77, v65
	v_fma_f32 v64, -v64, v76, v73
	v_div_fmas_f32 v64, v64, v65, v76
	v_div_fixup_f32 v65, v64, v88, 1.0
	v_div_scale_f32 v64, s[10:11], v85, v85, 1.0
	v_rcp_f32_e32 v73, v64
	v_cvt_pk_bf16_f32 v47, v48, v49
	v_cvt_pk_bf16_f32 v39, v40, v41
	v_pk_mul_f32 v[32:33], v[32:33], v[62:63]
	v_fma_f32 v76, -v64, v73, 1.0
	v_fmac_f32_e32 v73, v76, v73
	v_div_scale_f32 v76, vcc, 1.0, v85, 1.0
	v_mul_f32_e32 v77, v76, v73
	v_fma_f32 v78, -v64, v77, v76
	v_fmac_f32_e32 v77, v78, v73
	v_fma_f32 v64, -v64, v77, v76
	v_div_fmas_f32 v64, v64, v73, v77
	v_div_fixup_f32 v64, v64, v85, 1.0
	v_pk_mul_f32 v[58:59], v[58:59], v[64:65]
	v_pk_mul_f32 v[42:43], v[42:43], v[64:65]
	v_cvt_pk_bf16_f32 v58, v58, v59
	v_div_scale_f32 v59, s[10:11], v72, v72, 1.0
	v_rcp_f32_e32 v73, v59
	v_pk_mul_f32 v[34:35], v[34:35], v[64:65]
	v_cvt_pk_bf16_f32 v42, v42, v43
	v_cvt_pk_bf16_f32 v34, v34, v35
	v_fma_f32 v76, -v59, v73, 1.0
	v_fmac_f32_e32 v73, v76, v73
	v_div_scale_f32 v76, vcc, 1.0, v72, 1.0
	v_mul_f32_e32 v77, v76, v73
	v_fma_f32 v78, -v59, v77, v76
	v_fmac_f32_e32 v77, v78, v73
	v_fma_f32 v59, -v59, v77, v76
	v_div_fmas_f32 v59, v59, v73, v77
	v_div_fixup_f32 v73, v59, v72, 1.0
	v_div_scale_f32 v59, s[10:11], v86, v86, 1.0
	v_rcp_f32_e32 v72, v59
	v_pk_mul_f32 v[50:51], v[50:51], v[64:65]
	v_pk_mul_f32 v[26:27], v[26:27], v[64:65]
	v_cvt_pk_bf16_f32 v50, v50, v51
	v_fma_f32 v76, -v59, v72, 1.0
	v_fmac_f32_e32 v72, v76, v72
	v_div_scale_f32 v76, vcc, 1.0, v86, 1.0
	v_mul_f32_e32 v77, v76, v72
	v_fma_f32 v78, -v59, v77, v76
	v_fmac_f32_e32 v77, v78, v72
	v_fma_f32 v59, -v59, v77, v76
	v_div_fmas_f32 v59, v59, v72, v77
	v_div_fixup_f32 v72, v59, v86, 1.0
	v_pk_mul_f32 v[60:61], v[60:61], v[72:73]
	v_pk_mul_f32 v[44:45], v[44:45], v[72:73]
	v_cvt_pk_bf16_f32 v59, v60, v61
	v_lshlrev_b64 v[60:61], 14, v[68:69]
	v_lshl_add_u64 v[60:61], s[12:13], 0, v[60:61]
	v_pk_mul_f32 v[36:37], v[36:37], v[72:73]
	v_lshl_add_u64 v[68:69], v[60:61], 0, v[0:1]
	v_cvt_pk_bf16_f32 v43, v44, v45
	v_lshl_add_u64 v[44:45], v[60:61], 0, v[106:107]
	v_cvt_pk_bf16_f32 v35, v36, v37
	v_lshl_add_u64 v[36:37], v[60:61], 0, v[98:99]
	v_lshl_add_u64 v[68:69], v[68:69], 0, v[122:123]
	v_pk_mul_f32 v[52:53], v[52:53], v[72:73]
	v_lshl_add_u64 v[44:45], v[44:45], 0, v[122:123]
	v_lshl_add_u64 v[36:37], v[36:37], 0, v[122:123]
	global_store_dwordx2 v[68:69], v[70:71], off
	global_store_dwordx2 v[68:69], v[58:59], off offset:16
	v_cvt_pk_bf16_f32 v51, v52, v53
	global_store_dwordx2 v[68:69], v[54:55], off offset:2048
	global_store_dwordx2 v[68:69], v[50:51], off offset:2064
	global_store_dwordx2 v[44:45], v[46:47], off
	global_store_dwordx2 v[44:45], v[42:43], off offset:16
	global_store_dwordx2 v[36:37], v[38:39], off
	global_store_dwordx2 v[36:37], v[34:35], off offset:16
	v_add_u32_e32 v34, s5, v74
	v_lshl_or_b32 v34, v34, 5, v75
	v_ashrrev_i32_e32 v35, 31, v34
	v_pk_mul_f32 v[28:29], v[28:29], v[72:73]
	v_cvt_pk_bf16_f32 v26, v26, v27
	v_cvt_pk_bf16_f32 v27, v28, v29
	v_lshlrev_b64 v[28:29], 14, v[34:35]
	v_lshl_add_u64 v[28:29], s[12:13], 0, v[28:29]
	v_pk_mul_f32 v[10:11], v[10:11], v[64:65]
	v_pk_mul_f32 v[12:13], v[12:13], v[72:73]
	v_pk_mul_f32 v[2:3], v[2:3], v[64:65]
	v_pk_mul_f32 v[4:5], v[4:5], v[72:73]
	v_cvt_pk_bf16_f32 v30, v30, v31
	v_cvt_pk_bf16_f32 v31, v32, v33
	v_lshl_add_u64 v[32:33], v[28:29], 0, v[0:1]
	v_pk_mul_f32 v[22:23], v[22:23], v[66:67]
	v_pk_mul_f32 v[24:25], v[24:25], v[62:63]
	v_pk_mul_f32 v[14:15], v[14:15], v[66:67]
	v_pk_mul_f32 v[16:17], v[16:17], v[62:63]
	v_cvt_pk_bf16_f32 v10, v10, v11
	v_cvt_pk_bf16_f32 v11, v12, v13
	v_lshl_add_u64 v[12:13], v[28:29], 0, v[106:107]
	v_pk_mul_f32 v[6:7], v[6:7], v[66:67]
	v_pk_mul_f32 v[8:9], v[8:9], v[62:63]
	v_cvt_pk_bf16_f32 v2, v2, v3
	v_cvt_pk_bf16_f32 v3, v4, v5
	v_lshl_add_u64 v[4:5], v[28:29], 0, v[98:99]
	v_lshl_add_u64 v[32:33], v[32:33], 0, v[122:123]
	v_cvt_pk_bf16_f32 v22, v22, v23
	v_cvt_pk_bf16_f32 v23, v24, v25
	v_pk_mul_f32 v[18:19], v[18:19], v[64:65]
	v_pk_mul_f32 v[20:21], v[20:21], v[72:73]
	v_cvt_pk_bf16_f32 v14, v14, v15
	v_cvt_pk_bf16_f32 v15, v16, v17
	v_lshl_add_u64 v[12:13], v[12:13], 0, v[122:123]
	v_cvt_pk_bf16_f32 v6, v6, v7
	v_cvt_pk_bf16_f32 v7, v8, v9
	v_lshl_add_u64 v[4:5], v[4:5], 0, v[122:123]
	s_mov_b64 s[10:11], -1
	s_andn2_b64 vcc, exec, s[38:39]
	global_store_dwordx2 v[32:33], v[30:31], off
	global_store_dwordx2 v[32:33], v[26:27], off offset:16
	v_cvt_pk_bf16_f32 v18, v18, v19
	v_cvt_pk_bf16_f32 v19, v20, v21
	global_store_dwordx2 v[32:33], v[22:23], off offset:2048
	global_store_dwordx2 v[32:33], v[18:19], off offset:2064
	global_store_dwordx2 v[12:13], v[14:15], off
	global_store_dwordx2 v[12:13], v[10:11], off offset:16
	global_store_dwordx2 v[4:5], v[6:7], off
	global_store_dwordx2 v[4:5], v[2:3], off offset:16
	s_cbranch_vccnz .LBB0_165
	s_andn2_b64 vcc, exec, s[36:37]
	s_cbranch_vccnz .LBB0_164
	s_barrier
	s_branch .LBB0_164
